# v11 + attention epilogue cross-half exchanges via v_permlane32_swap_b32 instead of ds_bpermute_b32 + selects (DPP/permlane lever, no LDS round trips)
# speedup vs baseline: 1.0111x; 1.0111x over previous
; __device__ __forceinline__ void attn_unit(int b, int h, int qb, bf16_t* Q, const bf16_t* __restrict__ K, const bf16_t* __restrict__ Vt, const bf16_t* __restrict__ Z, const float* __restrict__ hg, float lam, ...
;     ...
;     const float l1 = lsum[0] + __shfl_xor(lsum[0], 32), l2 = lsum[1] + __shfl_xor(lsum[1], 32);
;     const float i1 = 1.f / l1, i2 = lam / l2;
;     float ss = 0.f;
; #pragma unroll
;     for (int d = 0; d < 4; ++d)
; #pragma unroll
;         for (int r = 0; r < 16; ++r) { const float v = o[0][d][r] * i1 - o[1][d][r] * i2; o[0][d][r] = v; ss += v * v; }
;     ...
;             const u32x4 zl = *(const u32x4*)(Z + offw + 32 * d + 16 * ip + 8 * hi_l);
.LBB0_236:
	v_ashrrev_i32_e32 v138, 5, v230
	v_and_or_b32 v140, v230, 31, s82
	v_mov_b32_e32 v141, s83
	v_lshlrev_b64 v[140:141], 11, v[140:141]
	v_lshl_add_u64 v[140:141], v[140:141], 0, s[18:19]
	v_lshlrev_b32_e32 v138, 3, v138
	v_lshlrev_b64 v[140:141], 1, v[140:141]
	v_ashrrev_i32_e32 v139, 31, v138
	v_lshl_add_u64 v[140:141], s[28:29], 0, v[140:141]
	v_lshlrev_b64 v[138:139], 1, v[138:139]
	v_lshl_add_u64 v[140:141], v[140:141], 0, v[138:139]
	global_load_dwordx4 v[146:149], v[140:141], off
	global_load_dwordx4 v[150:153], v[140:141], off offset:32
	global_load_dwordx4 v[154:157], v[140:141], off offset:64
	global_load_dwordx4 v[158:161], v[140:141], off offset:96
	global_load_dwordx4 v[162:165], v[140:141], off offset:128
	global_load_dwordx4 v[166:169], v[140:141], off offset:160
	global_load_dwordx4 v[170:173], v[140:141], off offset:192
	global_load_dwordx4 v[174:177], v[140:141], off offset:224
	ds_bpermute_b32 v128, v217, v224
	ds_bpermute_b32 v129, v217, v225
	s_waitcnt lgkmcnt(0)
	v_pk_add_f32 v[128:129], v[224:225], v[128:129]
	s_nop 0
	v_div_scale_f32 v130, s[8:9], v129, v129, s71
	v_rcp_f32_e32 v132, v130
	v_div_scale_f32 v131, vcc, s71, v129, s71
	v_div_scale_f32 v133, s[8:9], v128, v128, 1.0
	v_fma_f32 v135, -v130, v132, 1.0
	v_fmac_f32_e32 v132, v135, v132
	v_mul_f32_e32 v135, v131, v132
	v_rcp_f32_e32 v134, v133
	v_fma_f32 v136, -v130, v135, v131
	v_fmac_f32_e32 v135, v136, v132
	v_fma_f32 v130, -v130, v135, v131
	v_div_fmas_f32 v130, v130, v132, v135
	v_div_fixup_f32 v129, v130, v129, s71
	v_fma_f32 v130, -v133, v134, 1.0
	v_fmac_f32_e32 v134, v130, v134
	v_div_scale_f32 v130, vcc, 1.0, v128, 1.0
	v_mul_f32_e32 v131, v130, v134
	v_fma_f32 v132, -v133, v131, v130
	v_fmac_f32_e32 v131, v132, v134
	v_fma_f32 v130, -v133, v131, v130
	v_div_fmas_f32 v130, v130, v134, v131
	v_div_fixup_f32 v128, v130, v128, 1.0
	v_mov_b32_e32 v131, v112
	v_mov_b32_e32 v112, v65
	v_mov_b32_e32 v130, v64
	v_pk_mul_f32 v[64:65], v[112:113], v[128:129]
	v_pk_mul_f32 v[130:131], v[130:131], v[128:129]
	v_sub_f32_e32 v132, v64, v65
	v_mov_b32_e32 v64, v66
	v_mov_b32_e32 v65, v114
	v_pk_mul_f32 v[64:65], v[64:65], v[128:129]
	v_mov_b32_e32 v114, v67
	v_sub_f32_e32 v133, v64, v65
	v_pk_mul_f32 v[64:65], v[114:115], v[128:129]
	v_sub_f32_e32 v131, v130, v131
	v_sub_f32_e32 v134, v64, v65
	v_mov_b32_e32 v64, v68
	v_mov_b32_e32 v65, v116
	v_pk_mul_f32 v[64:65], v[64:65], v[128:129]
	v_mov_b32_e32 v116, v69
	v_sub_f32_e32 v135, v64, v65
	v_pk_mul_f32 v[64:65], v[116:117], v[128:129]
	s_nop 0
	v_sub_f32_e32 v136, v64, v65
	v_mov_b32_e32 v64, v70
	v_mov_b32_e32 v65, v118
	v_pk_mul_f32 v[64:65], v[64:65], v[128:129]
	v_mov_b32_e32 v118, v71
	v_sub_f32_e32 v130, v64, v65
	v_pk_mul_f32 v[64:65], v[118:119], v[128:129]
	s_nop 0
	v_sub_f32_e32 v119, v64, v65
	v_mov_b32_e32 v64, v72
	v_mov_b32_e32 v65, v120
	v_pk_mul_f32 v[64:65], v[64:65], v[128:129]
	v_mov_b32_e32 v120, v73
	v_sub_f32_e32 v118, v64, v65
	v_pk_mul_f32 v[64:65], v[120:121], v[128:129]
	s_nop 0
	v_sub_f32_e32 v117, v64, v65
	v_mov_b32_e32 v64, v74
	v_mov_b32_e32 v65, v122
	v_pk_mul_f32 v[64:65], v[64:65], v[128:129]
	v_mov_b32_e32 v122, v75
	v_sub_f32_e32 v116, v64, v65
	v_pk_mul_f32 v[64:65], v[122:123], v[128:129]
	s_nop 0
	v_sub_f32_e32 v115, v64, v65
	v_mov_b32_e32 v64, v76
	v_mov_b32_e32 v65, v124
	v_pk_mul_f32 v[64:65], v[64:65], v[128:129]
	v_mov_b32_e32 v124, v77
	v_sub_f32_e32 v114, v64, v65
	v_pk_mul_f32 v[64:65], v[124:125], v[128:129]
	s_nop 0
	v_sub_f32_e32 v113, v64, v65
	v_mov_b32_e32 v64, v78
	v_mov_b32_e32 v65, v126
	v_pk_mul_f32 v[64:65], v[64:65], v[128:129]
	v_mov_b32_e32 v126, v79
	v_sub_f32_e32 v112, v64, v65
	v_pk_mul_f32 v[64:65], v[126:127], v[128:129]
	s_nop 0
	v_sub_f32_e32 v78, v64, v65
	v_mov_b32_e32 v65, v96
	v_mov_b32_e32 v96, v49
	v_mov_b32_e32 v64, v48
	v_pk_mul_f32 v[48:49], v[96:97], v[128:129]
	v_pk_mul_f32 v[64:65], v[64:65], v[128:129]
	v_sub_f32_e32 v76, v48, v49
	v_mov_b32_e32 v48, v50
	v_mov_b32_e32 v49, v98
	v_pk_mul_f32 v[48:49], v[48:49], v[128:129]
	v_mov_b32_e32 v98, v51
	v_sub_f32_e32 v75, v48, v49
	v_pk_mul_f32 v[48:49], v[98:99], v[128:129]
	v_sub_f32_e32 v77, v64, v65
	v_sub_f32_e32 v74, v48, v49
	v_mov_b32_e32 v48, v52
	v_mov_b32_e32 v49, v100
	v_pk_mul_f32 v[48:49], v[48:49], v[128:129]
	v_mov_b32_e32 v100, v53
	v_sub_f32_e32 v73, v48, v49
	v_pk_mul_f32 v[48:49], v[100:101], v[128:129]
	s_nop 0
	v_sub_f32_e32 v72, v48, v49
	v_mov_b32_e32 v48, v54
	v_mov_b32_e32 v49, v102
	v_pk_mul_f32 v[48:49], v[48:49], v[128:129]
	v_mov_b32_e32 v102, v55
	v_sub_f32_e32 v71, v48, v49
	v_pk_mul_f32 v[48:49], v[102:103], v[128:129]
	s_nop 0
	v_sub_f32_e32 v70, v48, v49
	v_mov_b32_e32 v48, v56
	v_mov_b32_e32 v49, v104
	v_pk_mul_f32 v[48:49], v[48:49], v[128:129]
	v_mov_b32_e32 v104, v57
	v_sub_f32_e32 v69, v48, v49
	v_pk_mul_f32 v[48:49], v[104:105], v[128:129]
	s_nop 0
	v_sub_f32_e32 v68, v48, v49
	v_mov_b32_e32 v48, v58
	v_mov_b32_e32 v49, v106
	v_pk_mul_f32 v[48:49], v[48:49], v[128:129]
	v_mov_b32_e32 v106, v59
	v_sub_f32_e32 v67, v48, v49
	v_pk_mul_f32 v[48:49], v[106:107], v[128:129]
	s_nop 0
	v_sub_f32_e32 v66, v48, v49
	v_mov_b32_e32 v48, v60
	v_mov_b32_e32 v49, v108
	v_pk_mul_f32 v[48:49], v[48:49], v[128:129]
	v_mov_b32_e32 v108, v61
	v_sub_f32_e32 v65, v48, v49
	v_pk_mul_f32 v[48:49], v[108:109], v[128:129]
	s_nop 0
	v_sub_f32_e32 v64, v48, v49
	v_mov_b32_e32 v48, v62
	v_mov_b32_e32 v49, v110
	v_pk_mul_f32 v[48:49], v[48:49], v[128:129]
	v_mov_b32_e32 v110, v63
	v_sub_f32_e32 v61, v48, v49
	v_pk_mul_f32 v[48:49], v[110:111], v[128:129]
	s_nop 0
	v_sub_f32_e32 v60, v48, v49
	v_mov_b32_e32 v49, v80
	v_mov_b32_e32 v80, v17
	v_mov_b32_e32 v48, v16
; __device__ __forceinline__ void attn_unit(int b, int h, int qb, bf16_t* Q, const bf16_t* __restrict__ K, const bf16_t* __restrict__ Vt, const bf16_t* __restrict__ Z, const float* __restrict__ hg, float lam, ...
;     ...
;     for (int d = 0; d < 4; ++d)
; #pragma unroll
;         for (int r = 0; r < 16; ++r) { const float v = o[0][d][r] * i1 - o[1][d][r] * i2; o[0][d][r] = v; ss += v * v; }
;     ss += __shfl_xor(ss, 32);
	v_pk_mul_f32 v[16:17], v[80:81], v[128:129]
	v_pk_mul_f32 v[48:49], v[48:49], v[128:129]
	v_sub_f32_e32 v58, v16, v17
	v_mov_b32_e32 v16, v18
	v_mov_b32_e32 v17, v82
	v_pk_mul_f32 v[16:17], v[16:17], v[128:129]
	v_mov_b32_e32 v82, v19
	v_sub_f32_e32 v57, v16, v17
	v_pk_mul_f32 v[16:17], v[82:83], v[128:129]
	v_sub_f32_e32 v59, v48, v49
	v_sub_f32_e32 v56, v16, v17
	v_mov_b32_e32 v16, v20
	v_mov_b32_e32 v17, v84
	v_pk_mul_f32 v[16:17], v[16:17], v[128:129]
	v_mov_b32_e32 v84, v21
	v_sub_f32_e32 v55, v16, v17
	v_pk_mul_f32 v[16:17], v[84:85], v[128:129]
	s_nop 0
	v_sub_f32_e32 v54, v16, v17
	v_mov_b32_e32 v16, v22
	v_mov_b32_e32 v17, v86
	v_pk_mul_f32 v[16:17], v[16:17], v[128:129]
	v_mov_b32_e32 v86, v23
	v_sub_f32_e32 v53, v16, v17
	v_pk_mul_f32 v[16:17], v[86:87], v[128:129]
	s_nop 0
	v_sub_f32_e32 v52, v16, v17
	v_mov_b32_e32 v16, v24
	v_mov_b32_e32 v17, v88
	v_pk_mul_f32 v[16:17], v[16:17], v[128:129]
	v_mov_b32_e32 v88, v25
	v_sub_f32_e32 v51, v16, v17
	v_pk_mul_f32 v[16:17], v[88:89], v[128:129]
	s_nop 0
	v_sub_f32_e32 v50, v16, v17
	v_mov_b32_e32 v16, v26
	v_mov_b32_e32 v17, v90
	v_pk_mul_f32 v[16:17], v[16:17], v[128:129]
	v_mov_b32_e32 v90, v27
	v_sub_f32_e32 v49, v16, v17
	v_pk_mul_f32 v[16:17], v[90:91], v[128:129]
	s_nop 0
	v_sub_f32_e32 v48, v16, v17
	v_mov_b32_e32 v16, v28
	v_mov_b32_e32 v17, v92
	v_pk_mul_f32 v[16:17], v[16:17], v[128:129]
	v_mov_b32_e32 v92, v29
	v_sub_f32_e32 v27, v16, v17
	v_pk_mul_f32 v[16:17], v[92:93], v[128:129]
	s_nop 0
	v_sub_f32_e32 v26, v16, v17
	v_mov_b32_e32 v16, v30
	v_mul_f32_e32 v30, v131, v131
	v_fmac_f32_e32 v30, v132, v132
	v_fmac_f32_e32 v30, v133, v133
	v_fmac_f32_e32 v30, v134, v134
	v_fmac_f32_e32 v30, v135, v135
	v_fmac_f32_e32 v30, v136, v136
	v_fmac_f32_e32 v30, v130, v130
	v_fmac_f32_e32 v30, v119, v119
	v_fmac_f32_e32 v30, v118, v118
	v_fmac_f32_e32 v30, v117, v117
	v_fmac_f32_e32 v30, v116, v116
	v_fmac_f32_e32 v30, v115, v115
	v_fmac_f32_e32 v30, v114, v114
	v_fmac_f32_e32 v30, v113, v113
	v_fmac_f32_e32 v30, v112, v112
	v_fmac_f32_e32 v30, v78, v78
	v_fmac_f32_e32 v30, v77, v77
	v_fmac_f32_e32 v30, v76, v76
	v_fmac_f32_e32 v30, v75, v75
	v_fmac_f32_e32 v30, v74, v74
	v_fmac_f32_e32 v30, v73, v73
	v_fmac_f32_e32 v30, v72, v72
	v_fmac_f32_e32 v30, v71, v71
	v_fmac_f32_e32 v30, v70, v70
	v_fmac_f32_e32 v30, v69, v69
	v_fmac_f32_e32 v30, v68, v68
	v_fmac_f32_e32 v30, v67, v67
	v_fmac_f32_e32 v30, v66, v66
	v_fmac_f32_e32 v30, v65, v65
	v_fmac_f32_e32 v30, v64, v64
	v_fmac_f32_e32 v30, v61, v61
	v_fmac_f32_e32 v30, v60, v60
	v_fmac_f32_e32 v30, v59, v59
	v_fmac_f32_e32 v30, v58, v58
	v_fmac_f32_e32 v30, v57, v57
	v_fmac_f32_e32 v30, v56, v56
	v_mov_b32_e32 v17, v94
	v_fmac_f32_e32 v30, v55, v55
	v_pk_mul_f32 v[16:17], v[16:17], v[128:129]
	v_mov_b32_e32 v94, v31
	v_fmac_f32_e32 v30, v54, v54
	v_sub_f32_e32 v25, v16, v17
	v_pk_mul_f32 v[16:17], v[94:95], v[128:129]
	v_fmac_f32_e32 v30, v53, v53
	v_sub_f32_e32 v24, v16, v17
	v_mov_b32_e32 v17, v32
	v_mov_b32_e32 v32, v1
	v_fmac_f32_e32 v30, v52, v52
	v_mov_b32_e32 v16, v0
	v_pk_mul_f32 v[0:1], v[32:33], v[128:129]
	v_fmac_f32_e32 v30, v51, v51
	v_sub_f32_e32 v22, v0, v1
	v_mov_b32_e32 v0, v2
	v_mov_b32_e32 v1, v34
	v_fmac_f32_e32 v30, v50, v50
	v_pk_mul_f32 v[0:1], v[0:1], v[128:129]
	v_mov_b32_e32 v34, v3
	v_fmac_f32_e32 v30, v49, v49
	v_sub_f32_e32 v21, v0, v1
	v_pk_mul_f32 v[0:1], v[34:35], v[128:129]
	v_fmac_f32_e32 v30, v48, v48
	v_sub_f32_e32 v20, v0, v1
	v_mov_b32_e32 v0, v4
	v_mov_b32_e32 v1, v36
	v_fmac_f32_e32 v30, v27, v27
	v_pk_mul_f32 v[0:1], v[0:1], v[128:129]
	v_mov_b32_e32 v36, v5
	v_fmac_f32_e32 v30, v26, v26
	v_pk_mul_f32 v[16:17], v[16:17], v[128:129]
	v_sub_f32_e32 v19, v0, v1
	v_pk_mul_f32 v[0:1], v[36:37], v[128:129]
	v_fmac_f32_e32 v30, v25, v25
	v_sub_f32_e32 v23, v16, v17
	v_sub_f32_e32 v18, v0, v1
	v_mov_b32_e32 v0, v6
	v_mov_b32_e32 v1, v38
	v_mov_b32_e32 v38, v7
	v_fmac_f32_e32 v30, v24, v24
	v_pk_mul_f32 v[0:1], v[0:1], v[128:129]
	v_pk_mul_f32 v[2:3], v[38:39], v[128:129]
	v_fmac_f32_e32 v30, v23, v23
	v_mov_b32_e32 v4, v2
	v_mov_b32_e32 v5, v0
	v_mov_b32_e32 v0, v3
	v_fmac_f32_e32 v30, v22, v22
	v_pk_add_f32 v[16:17], v[4:5], v[0:1] neg_lo:[0,1] neg_hi:[0,1]
	v_mov_b32_e32 v0, v8
	v_mov_b32_e32 v1, v40
	v_mov_b32_e32 v40, v9
	v_fmac_f32_e32 v30, v21, v21
	v_pk_mul_f32 v[0:1], v[0:1], v[128:129]
	v_pk_mul_f32 v[2:3], v[40:41], v[128:129]
	v_fmac_f32_e32 v30, v20, v20
	v_mov_b32_e32 v4, v2
	v_mov_b32_e32 v5, v0
	v_mov_b32_e32 v0, v3
	v_fmac_f32_e32 v30, v19, v19
	v_pk_mul_f32 v[28:29], v[16:17], v[16:17]
	v_pk_add_f32 v[6:7], v[4:5], v[0:1] neg_lo:[0,1] neg_hi:[0,1]
	v_mov_b32_e32 v0, v10
	v_mov_b32_e32 v1, v42
	v_mov_b32_e32 v42, v11
	v_fmac_f32_e32 v30, v18, v18
	v_pk_mul_f32 v[0:1], v[0:1], v[128:129]
	v_pk_mul_f32 v[2:3], v[42:43], v[128:129]
	v_add_f32_e32 v29, v29, v30
	v_pk_mul_f32 v[8:9], v[6:7], v[6:7]
	v_mov_b32_e32 v4, v2
	v_mov_b32_e32 v5, v0
	v_mov_b32_e32 v0, v3
	v_add_f32_e32 v28, v28, v29
	v_pk_add_f32 v[4:5], v[4:5], v[0:1] neg_lo:[0,1] neg_hi:[0,1]
	v_mov_b32_e32 v0, v129
	v_add_f32_e32 v9, v9, v28
	v_pk_mul_f32 v[10:11], v[4:5], v[4:5]
	v_pk_mul_f32 v[2:3], v[44:45], v[0:1] op_sel_hi:[1,0]
	v_add_f32_e32 v8, v8, v9
	v_pk_fma_f32 v[2:3], v[12:13], v[128:129], v[2:3] op_sel_hi:[1,0,1] neg_lo:[0,0,1] neg_hi:[0,0,1]
	v_add_f32_e32 v8, v11, v8
	v_pk_mul_f32 v[12:13], v[2:3], v[2:3]
	v_pk_mul_f32 v[0:1], v[46:47], v[0:1] op_sel_hi:[1,0]
	v_add_f32_e32 v8, v10, v8
	v_pk_fma_f32 v[0:1], v[14:15], v[128:129], v[0:1] op_sel_hi:[1,0,1] neg_lo:[0,0,1] neg_hi:[0,0,1]
	v_add_f32_e32 v8, v12, v8
	v_pk_mul_f32 v[14:15], v[0:1], v[0:1]
	v_add_f32_e32 v8, v13, v8
	v_add_f32_e32 v8, v14, v8
	v_add_f32_e32 v8, v15, v8
	ds_bpermute_b32 v9, v217, v8
	v_mov_b32_e32 v15, v230
	s_waitcnt lgkmcnt(0)
; __device__ __forceinline__ unsigned pk2(float lo, float hi) { return pg8::cvt_pk_bf16(lo, hi); }
; __device__ __forceinline__ float siluf_(float v) { return v * __builtin_amdgcn_rcpf(1.f + __builtin_amdgcn_exp2f(-LOG2E * v)); }
; __device__ __forceinline__ void attn_unit(int b, int h, int qb, bf16_t* Q, const bf16_t* __restrict__ K, const bf16_t* __restrict__ Vt, const bf16_t* __restrict__ Z, const float* __restrict__ hg, float lam, ...
;     ...
;     const float rs = rsqrtf(ss * (1.f / 128.f) + EPS) * (1.f - LAM0);
;     int lane_l = lane; asm volatile("" : "+v"(lane_l));
;     const size_t off = (rowbase + qw0 + (lane_l & 31)) * BR + h * 128 + 4 * (lane_l >> 5);
;     __builtin_amdgcn_sched_barrier(0);
;     const int hi_l = lane_l >> 5;
;     const size_t offw = off - 4 * hi_l;
; #pragma unroll
;     for (int d = 0; d < 4; ++d)
; #pragma unroll
;         for (int ip = 0; ip < 2; ++ip) { __builtin_amdgcn_sched_barrier(0);
;             u32x2 w[2];
;             const u32x4 zl = *(const u32x4*)(Z + offw + 32 * d + 16 * ip + 8 * hi_l);
;             const unsigned zsx = hi_l ? zl.x : zl.z, zsy = hi_l ? zl.y : zl.w;
;             const unsigned zrx = __shfl_xor(zsx, 32), zry = __shfl_xor(zsy, 32);
; #pragma unroll
;             for (int k = 0; k < 2; ++k) { const int i = 2 * ip + k, e = 32 * d + 8 * i;
;                 const f32x4 g4 = *(const f32x4*)(hg + e + 4 * hi_l);
;                 const u32x2 z2 = (k == 0) ? (hi_l ? (u32x2){zrx, zry} : (u32x2){zl.x, zl.y}) : (hi_l ? (u32x2){zl.z, zl.w} : (u32x2){zrx, zry});
;                 const float v0 = o[0][d][4 * i] * rs * g4[0] * siluf_(bflo(z2.x)), v1 = o[0][d][4 * i + 1] * rs * g4[1] * siluf_(bfhi(z2.x));
;                 const float v2 = o[0][d][4 * i + 2] * rs * g4[2] * siluf_(bflo(z2.y)), v3 = o[0][d][4 * i + 3] * rs * g4[3] * siluf_(bfhi(z2.y));
;                 w[k] = (u32x2){pk2(v0, v1), pk2(v2, v3)}; }
;             const u32x2 snd = hi_l ? w[0] : w[1];
;             const unsigned rx = __shfl_xor(snd.x, 32), ry = __shfl_xor(snd.y, 32);
;             const u32x4 st = hi_l ? (u32x4){rx, ry, w[1].x, w[1].y} : (u32x4){w[0].x, w[0].y, rx, ry};
;             *(u32x4*)(Q + offw + 32 * d + 16 * ip + 8 * hi_l) = st; }
	v_add_f32_e32 v8, v8, v9
	v_fmamk_f32 v8, v8, 0x3c000000, v245
	v_mul_f32_e32 v9, 0x4b800000, v8
	v_cmp_gt_f32_e32 vcc, s81, v8
	v_ashrrev_i32_e32 v28, 5, v15
	v_lshlrev_b32_e32 v137, 4, v28
	v_add_u32_e32 v137, 0x11100, v137
	v_lshlrev_b32_e32 v10, 2, v28
	v_cndmask_b32_e32 v8, v8, v9, vcc
	v_rsq_f32_e32 v8, v8
	v_ashrrev_i32_e32 v11, 31, v10
	v_mul_f32_e32 v9, 0x45800000, v8
	v_cndmask_b32_e32 v8, v8, v9, vcc
	v_mul_f32_e32 v14, 0x3f4ccccd, v8
	v_and_or_b32 v8, v15, 31, s82
	v_mov_b32_e32 v9, s83
	v_lshlrev_b64 v[8:9], 11, v[8:9]
	v_lshl_add_u64 v[8:9], v[8:9], 0, s[18:19]
	v_lshlrev_b32_e32 v28, 3, v28
	v_lshlrev_b64 v[8:9], 1, v[8:9]
	v_ashrrev_i32_e32 v29, 31, v28
	v_lshl_add_u64 v[12:13], s[28:29], 0, v[8:9]
	v_lshlrev_b64 v[28:29], 1, v[28:29]
	v_lshl_add_u64 v[8:9], s[34:35], 0, v[8:9]
	v_lshl_add_u64 v[12:13], v[12:13], 0, v[28:29]
	v_cmp_gt_u32_e32 vcc, 32, v15
	v_lshl_add_u64 v[10:11], v[10:11], 2, s[54:55]
	v_lshl_add_u64 v[8:9], v[8:9], 0, v[28:29]
	ds_read_b128 v[32:35], v137
	v_mul_f32_e32 v37, v131, v14
	v_mul_f32_e32 v39, v132, v14
	v_mul_f32_e32 v41, v133, v14
	v_mul_f32_e32 v43, v134, v14
	s_waitcnt vmcnt(7)
	v_mov_b32_e32 v28, v146
	v_mov_b32_e32 v29, v147
	v_mov_b32_e32 v30, v148
	v_mov_b32_e32 v31, v149
	s_nop 1
	v_permlane32_swap_b32_e32 v28, v30
	v_permlane32_swap_b32_e32 v29, v31
	s_waitcnt lgkmcnt(0)
	v_mov_b32_e32 v45, v32
	v_mov_b32_e32 v47, v34
	v_lshlrev_b32_e32 v36, 16, v28
	v_and_b32_e32 v38, 0xffff0000, v28
	v_lshlrev_b32_e32 v40, 16, v29
	v_and_b32_e32 v42, 0xffff0000, v29
	v_mul_f32_e32 v28, 0xbfb8aa3b, v36
	v_mul_f32_e32 v29, 0xbfb8aa3b, v38
	v_mul_f32_e32 v32, 0xbfb8aa3b, v40
	v_mul_f32_e32 v34, 0xbfb8aa3b, v42
	v_exp_f32_e32 v28, v28
	v_exp_f32_e32 v29, v29
	v_exp_f32_e32 v32, v32
	v_exp_f32_e32 v34, v34
	v_add_f32_e32 v28, 1.0, v28
	v_add_f32_e32 v29, 1.0, v29
	v_add_f32_e32 v46, 1.0, v32
	v_add_f32_e32 v34, 1.0, v34
	v_rcp_f32_e32 v44, v28
	v_rcp_f32_e32 v32, v29
	v_rcp_f32_e32 v46, v46
	v_rcp_f32_e32 v34, v34
	v_pk_mul_f32 v[28:29], v[44:45], v[36:37]
	v_pk_mul_f32 v[32:33], v[32:33], v[38:39]
	v_pk_mul_f32 v[36:37], v[46:47], v[40:41]
	v_pk_mul_f32 v[34:35], v[34:35], v[42:43]
	v_mul_f32_e32 v28, v28, v29
	v_mul_f32_e32 v29, v32, v33
	v_mul_f32_e32 v32, v36, v37
	v_mul_f32_e32 v33, v34, v35
	v_cvt_pk_bf16_f32 v44, v28, v29
	v_cvt_pk_bf16_f32 v45, v32, v33
	ds_read_b128 v[32:35], v137 offset:32
	v_mov_b32_e32 v15, v30
	v_lshlrev_b32_e32 v28, 16, v15
	v_lshlrev_b32_e32 v38, 16, v31
	v_and_b32_e32 v36, 0xffff0000, v15
	v_and_b32_e32 v40, 0xffff0000, v31
	v_mul_f32_e32 v15, 0xbfb8aa3b, v28
	v_mul_f32_e32 v31, 0xbfb8aa3b, v38
	v_mul_f32_e32 v30, 0xbfb8aa3b, v36
	v_mul_f32_e32 v42, 0xbfb8aa3b, v40
	v_exp_f32_e32 v15, v15
	v_exp_f32_e32 v31, v31
	v_exp_f32_e32 v30, v30
	v_exp_f32_e32 v42, v42
	v_add_f32_e32 v15, 1.0, v15
	v_add_f32_e32 v31, 1.0, v31
	v_add_f32_e32 v43, 1.0, v30
	v_add_f32_e32 v46, 1.0, v42
	v_rcp_f32_e32 v30, v15
	v_rcp_f32_e32 v42, v31
	v_mul_f32_e32 v29, v135, v14
	v_mul_f32_e32 v39, v130, v14
	v_mul_f32_e32 v37, v136, v14
	v_mul_f32_e32 v41, v119, v14
	s_waitcnt lgkmcnt(0)
	v_mov_b32_e32 v31, v32
	v_rcp_f32_e32 v32, v43
	v_mov_b32_e32 v43, v34
	v_rcp_f32_e32 v34, v46
	v_pk_mul_f32 v[28:29], v[30:31], v[28:29]
	v_pk_mul_f32 v[30:31], v[42:43], v[38:39]
	v_mul_f32_e32 v15, v28, v29
	v_mul_f32_e32 v38, v30, v31
	v_pk_mul_f32 v[28:29], v[32:33], v[36:37]
	v_pk_mul_f32 v[30:31], v[34:35], v[40:41]
	v_mul_f32_e32 v28, v28, v29
	v_mul_f32_e32 v29, v30, v31
	v_cvt_pk_bf16_f32 v15, v15, v28
	v_cvt_pk_bf16_f32 v29, v38, v29
	s_nop 0
	v_mov_b32_e32 v31, v29
	v_mov_b32_e32 v30, v15
	v_mov_b32_e32 v28, v44
	v_mov_b32_e32 v29, v45
	s_nop 1
	v_permlane32_swap_b32_e32 v28, v30
	v_permlane32_swap_b32_e32 v29, v31
	global_store_dwordx4 v[8:9], v[28:31], off
	s_nop 0
	ds_read_b128 v[32:35], v137 offset:64
	v_mul_f32_e32 v37, v118, v14
	v_mul_f32_e32 v39, v117, v14
	v_mul_f32_e32 v41, v116, v14
	v_mul_f32_e32 v43, v115, v14
	s_waitcnt vmcnt(7)
	v_mov_b32_e32 v28, v150
	v_mov_b32_e32 v29, v151
	v_mov_b32_e32 v30, v152
	v_mov_b32_e32 v31, v153
	s_nop 1
	v_permlane32_swap_b32_e32 v28, v30
	v_permlane32_swap_b32_e32 v29, v31
	s_waitcnt lgkmcnt(0)
	v_mov_b32_e32 v45, v32
	v_mov_b32_e32 v47, v34
	v_lshlrev_b32_e32 v36, 16, v28
	v_and_b32_e32 v38, 0xffff0000, v28
	v_lshlrev_b32_e32 v40, 16, v29
	v_and_b32_e32 v42, 0xffff0000, v29
	v_mul_f32_e32 v28, 0xbfb8aa3b, v36
	v_mul_f32_e32 v29, 0xbfb8aa3b, v38
	v_mul_f32_e32 v32, 0xbfb8aa3b, v40
	v_mul_f32_e32 v34, 0xbfb8aa3b, v42
	v_exp_f32_e32 v28, v28
	v_exp_f32_e32 v29, v29
	v_exp_f32_e32 v32, v32
	v_exp_f32_e32 v34, v34
	v_add_f32_e32 v28, 1.0, v28
	v_add_f32_e32 v29, 1.0, v29
	v_add_f32_e32 v46, 1.0, v32
	v_add_f32_e32 v34, 1.0, v34
	v_rcp_f32_e32 v44, v28
	v_rcp_f32_e32 v32, v29
	v_rcp_f32_e32 v46, v46
	v_rcp_f32_e32 v34, v34
	v_pk_mul_f32 v[28:29], v[44:45], v[36:37]
	v_pk_mul_f32 v[32:33], v[32:33], v[38:39]
	v_pk_mul_f32 v[36:37], v[46:47], v[40:41]
	v_pk_mul_f32 v[34:35], v[34:35], v[42:43]
	v_mul_f32_e32 v28, v28, v29
	v_mul_f32_e32 v29, v32, v33
	v_mul_f32_e32 v32, v36, v37
	v_mul_f32_e32 v33, v34, v35
	v_cvt_pk_bf16_f32 v44, v28, v29
	v_cvt_pk_bf16_f32 v45, v32, v33
	ds_read_b128 v[32:35], v137 offset:96
	v_mov_b32_e32 v15, v30
	v_lshlrev_b32_e32 v28, 16, v15
	v_lshlrev_b32_e32 v38, 16, v31
	v_and_b32_e32 v36, 0xffff0000, v15
	v_and_b32_e32 v40, 0xffff0000, v31
	v_mul_f32_e32 v15, 0xbfb8aa3b, v28
	v_mul_f32_e32 v31, 0xbfb8aa3b, v38
	v_mul_f32_e32 v30, 0xbfb8aa3b, v36
	v_mul_f32_e32 v42, 0xbfb8aa3b, v40
	v_exp_f32_e32 v15, v15
	v_exp_f32_e32 v31, v31
	v_exp_f32_e32 v30, v30
	v_exp_f32_e32 v42, v42
	v_add_f32_e32 v15, 1.0, v15
	v_add_f32_e32 v31, 1.0, v31
	v_add_f32_e32 v43, 1.0, v30
	v_add_f32_e32 v46, 1.0, v42
	v_rcp_f32_e32 v30, v15
	v_rcp_f32_e32 v42, v31
	v_mul_f32_e32 v29, v114, v14
	v_mul_f32_e32 v39, v112, v14
	v_mul_f32_e32 v37, v113, v14
	v_mul_f32_e32 v41, v78, v14
	s_waitcnt lgkmcnt(0)
; __device__ __forceinline__ unsigned pk2(float lo, float hi) { return pg8::cvt_pk_bf16(lo, hi); }
; __device__ __forceinline__ float siluf_(float v) { return v * __builtin_amdgcn_rcpf(1.f + __builtin_amdgcn_exp2f(-LOG2E * v)); }
; __device__ __forceinline__ void attn_unit(int b, int h, int qb, bf16_t* Q, const bf16_t* __restrict__ K, const bf16_t* __restrict__ Vt, const bf16_t* __restrict__ Z, const float* __restrict__ hg, float lam, ...
;     ...
;         for (int ip = 0; ip < 2; ++ip) { __builtin_amdgcn_sched_barrier(0);
;             u32x2 w[2];
;             const u32x4 zl = *(const u32x4*)(Z + offw + 32 * d + 16 * ip + 8 * hi_l);
;             const unsigned zsx = hi_l ? zl.x : zl.z, zsy = hi_l ? zl.y : zl.w;
;             const unsigned zrx = __shfl_xor(zsx, 32), zry = __shfl_xor(zsy, 32);
; #pragma unroll
;             for (int k = 0; k < 2; ++k) { const int i = 2 * ip + k, e = 32 * d + 8 * i;
;                 const f32x4 g4 = *(const f32x4*)(hg + e + 4 * hi_l);
;                 const u32x2 z2 = (k == 0) ? (hi_l ? (u32x2){zrx, zry} : (u32x2){zl.x, zl.y}) : (hi_l ? (u32x2){zl.z, zl.w} : (u32x2){zrx, zry});
;                 const float v0 = o[0][d][4 * i] * rs * g4[0] * siluf_(bflo(z2.x)), v1 = o[0][d][4 * i + 1] * rs * g4[1] * siluf_(bfhi(z2.x));
;                 const float v2 = o[0][d][4 * i + 2] * rs * g4[2] * siluf_(bflo(z2.y)), v3 = o[0][d][4 * i + 3] * rs * g4[3] * siluf_(bfhi(z2.y));
;                 w[k] = (u32x2){pk2(v0, v1), pk2(v2, v3)}; }
;             const u32x2 snd = hi_l ? w[0] : w[1];
;             const unsigned rx = __shfl_xor(snd.x, 32), ry = __shfl_xor(snd.y, 32);
;             const u32x4 st = hi_l ? (u32x4){rx, ry, w[1].x, w[1].y} : (u32x4){w[0].x, w[0].y, rx, ry};
;             *(u32x4*)(Q + offw + 32 * d + 16 * ip + 8 * hi_l) = st; }
	v_mov_b32_e32 v31, v32
	v_rcp_f32_e32 v32, v43
	v_mov_b32_e32 v43, v34
	v_rcp_f32_e32 v34, v46
	v_pk_mul_f32 v[28:29], v[30:31], v[28:29]
	v_pk_mul_f32 v[30:31], v[42:43], v[38:39]
	v_mul_f32_e32 v15, v28, v29
	v_mul_f32_e32 v38, v30, v31
	v_pk_mul_f32 v[28:29], v[32:33], v[36:37]
	v_pk_mul_f32 v[30:31], v[34:35], v[40:41]
	v_mul_f32_e32 v28, v28, v29
	v_mul_f32_e32 v29, v30, v31
	v_cvt_pk_bf16_f32 v15, v15, v28
	v_cvt_pk_bf16_f32 v29, v38, v29
	s_nop 0
	v_mov_b32_e32 v31, v29
	v_mov_b32_e32 v30, v15
	v_mov_b32_e32 v28, v44
	v_mov_b32_e32 v29, v45
	s_nop 1
	v_permlane32_swap_b32_e32 v28, v30
	v_permlane32_swap_b32_e32 v29, v31
	global_store_dwordx4 v[8:9], v[28:31], off offset:32
	s_nop 0
	ds_read_b128 v[32:35], v137 offset:128
	v_mul_f32_e32 v37, v77, v14
	v_mul_f32_e32 v39, v76, v14
	v_mul_f32_e32 v41, v75, v14
	v_mul_f32_e32 v43, v74, v14
	s_waitcnt vmcnt(7)
	v_mov_b32_e32 v28, v154
	v_mov_b32_e32 v29, v155
	v_mov_b32_e32 v30, v156
	v_mov_b32_e32 v31, v157
	s_nop 1
	v_permlane32_swap_b32_e32 v28, v30
	v_permlane32_swap_b32_e32 v29, v31
	s_waitcnt lgkmcnt(0)
	v_mov_b32_e32 v45, v32
	v_mov_b32_e32 v47, v34
	v_lshlrev_b32_e32 v36, 16, v28
	v_and_b32_e32 v38, 0xffff0000, v28
	v_lshlrev_b32_e32 v40, 16, v29
	v_and_b32_e32 v42, 0xffff0000, v29
	v_mul_f32_e32 v28, 0xbfb8aa3b, v36
	v_mul_f32_e32 v29, 0xbfb8aa3b, v38
	v_mul_f32_e32 v32, 0xbfb8aa3b, v40
	v_mul_f32_e32 v34, 0xbfb8aa3b, v42
	v_exp_f32_e32 v28, v28
	v_exp_f32_e32 v29, v29
	v_exp_f32_e32 v32, v32
	v_exp_f32_e32 v34, v34
	v_add_f32_e32 v28, 1.0, v28
	v_add_f32_e32 v29, 1.0, v29
	v_add_f32_e32 v46, 1.0, v32
	v_add_f32_e32 v34, 1.0, v34
	v_rcp_f32_e32 v44, v28
	v_rcp_f32_e32 v32, v29
	v_rcp_f32_e32 v46, v46
	v_rcp_f32_e32 v34, v34
	v_pk_mul_f32 v[28:29], v[44:45], v[36:37]
	v_pk_mul_f32 v[32:33], v[32:33], v[38:39]
	v_pk_mul_f32 v[36:37], v[46:47], v[40:41]
	v_pk_mul_f32 v[34:35], v[34:35], v[42:43]
	v_mul_f32_e32 v28, v28, v29
	v_mul_f32_e32 v29, v32, v33
	v_mul_f32_e32 v32, v36, v37
	v_mul_f32_e32 v33, v34, v35
	v_cvt_pk_bf16_f32 v44, v28, v29
	v_cvt_pk_bf16_f32 v45, v32, v33
	ds_read_b128 v[32:35], v137 offset:160
	v_mov_b32_e32 v15, v30
	v_lshlrev_b32_e32 v28, 16, v15
	v_lshlrev_b32_e32 v38, 16, v31
	v_and_b32_e32 v36, 0xffff0000, v15
	v_and_b32_e32 v40, 0xffff0000, v31
	v_mul_f32_e32 v15, 0xbfb8aa3b, v28
	v_mul_f32_e32 v31, 0xbfb8aa3b, v38
	v_mul_f32_e32 v30, 0xbfb8aa3b, v36
	v_mul_f32_e32 v42, 0xbfb8aa3b, v40
	v_exp_f32_e32 v15, v15
	v_exp_f32_e32 v31, v31
	v_exp_f32_e32 v30, v30
	v_exp_f32_e32 v42, v42
	v_add_f32_e32 v15, 1.0, v15
	v_add_f32_e32 v31, 1.0, v31
	v_add_f32_e32 v43, 1.0, v30
	v_add_f32_e32 v46, 1.0, v42
	v_rcp_f32_e32 v30, v15
	v_rcp_f32_e32 v42, v31
	v_mul_f32_e32 v29, v73, v14
	v_mul_f32_e32 v39, v71, v14
	v_mul_f32_e32 v37, v72, v14
	v_mul_f32_e32 v41, v70, v14
	s_waitcnt lgkmcnt(0)
	v_mov_b32_e32 v31, v32
	v_rcp_f32_e32 v32, v43
	v_mov_b32_e32 v43, v34
	v_rcp_f32_e32 v34, v46
	v_pk_mul_f32 v[28:29], v[30:31], v[28:29]
	v_pk_mul_f32 v[30:31], v[42:43], v[38:39]
	v_mul_f32_e32 v15, v28, v29
	v_mul_f32_e32 v38, v30, v31
	v_pk_mul_f32 v[28:29], v[32:33], v[36:37]
	v_pk_mul_f32 v[30:31], v[34:35], v[40:41]
	v_mul_f32_e32 v28, v28, v29
	v_mul_f32_e32 v29, v30, v31
	v_cvt_pk_bf16_f32 v15, v15, v28
	v_cvt_pk_bf16_f32 v29, v38, v29
	s_nop 0
	v_mov_b32_e32 v31, v29
	v_mov_b32_e32 v30, v15
	v_mov_b32_e32 v28, v44
	v_mov_b32_e32 v29, v45
	s_nop 1
	v_permlane32_swap_b32_e32 v28, v30
	v_permlane32_swap_b32_e32 v29, v31
	global_store_dwordx4 v[8:9], v[28:31], off offset:64
	s_nop 0
	ds_read_b128 v[32:35], v137 offset:192
	v_mul_f32_e32 v37, v69, v14
	v_mul_f32_e32 v39, v68, v14
	v_mul_f32_e32 v41, v67, v14
	v_mul_f32_e32 v43, v66, v14
	s_waitcnt vmcnt(7)
	v_mov_b32_e32 v28, v158
	v_mov_b32_e32 v29, v159
	v_mov_b32_e32 v30, v160
	v_mov_b32_e32 v31, v161
	s_nop 1
	v_permlane32_swap_b32_e32 v28, v30
	v_permlane32_swap_b32_e32 v29, v31
	s_waitcnt lgkmcnt(0)
	v_mov_b32_e32 v45, v32
	v_mov_b32_e32 v47, v34
	v_lshlrev_b32_e32 v36, 16, v28
	v_and_b32_e32 v38, 0xffff0000, v28
	v_lshlrev_b32_e32 v40, 16, v29
	v_and_b32_e32 v42, 0xffff0000, v29
	v_mul_f32_e32 v28, 0xbfb8aa3b, v36
	v_mul_f32_e32 v29, 0xbfb8aa3b, v38
	v_mul_f32_e32 v32, 0xbfb8aa3b, v40
	v_mul_f32_e32 v34, 0xbfb8aa3b, v42
	v_exp_f32_e32 v28, v28
	v_exp_f32_e32 v29, v29
	v_exp_f32_e32 v32, v32
	v_exp_f32_e32 v34, v34
	v_add_f32_e32 v28, 1.0, v28
	v_add_f32_e32 v29, 1.0, v29
	v_add_f32_e32 v46, 1.0, v32
	v_add_f32_e32 v34, 1.0, v34
	v_rcp_f32_e32 v44, v28
	v_rcp_f32_e32 v32, v29
	v_rcp_f32_e32 v46, v46
	v_rcp_f32_e32 v34, v34
	v_pk_mul_f32 v[28:29], v[44:45], v[36:37]
	v_pk_mul_f32 v[32:33], v[32:33], v[38:39]
	v_pk_mul_f32 v[36:37], v[46:47], v[40:41]
	v_pk_mul_f32 v[34:35], v[34:35], v[42:43]
	v_mul_f32_e32 v28, v28, v29
	v_mul_f32_e32 v29, v32, v33
	v_mul_f32_e32 v32, v36, v37
	v_mul_f32_e32 v33, v34, v35
	v_cvt_pk_bf16_f32 v44, v28, v29
	v_cvt_pk_bf16_f32 v45, v32, v33
	ds_read_b128 v[32:35], v137 offset:224
	v_mov_b32_e32 v15, v30
	v_lshlrev_b32_e32 v28, 16, v15
	v_lshlrev_b32_e32 v38, 16, v31
	v_and_b32_e32 v36, 0xffff0000, v15
	v_and_b32_e32 v40, 0xffff0000, v31
	v_mul_f32_e32 v15, 0xbfb8aa3b, v28
	v_mul_f32_e32 v31, 0xbfb8aa3b, v38
	v_mul_f32_e32 v30, 0xbfb8aa3b, v36
	v_mul_f32_e32 v42, 0xbfb8aa3b, v40
	v_exp_f32_e32 v15, v15
	v_exp_f32_e32 v31, v31
	v_exp_f32_e32 v30, v30
	v_exp_f32_e32 v42, v42
	v_add_f32_e32 v15, 1.0, v15
	v_add_f32_e32 v31, 1.0, v31
	v_add_f32_e32 v43, 1.0, v30
	v_add_f32_e32 v46, 1.0, v42
	v_rcp_f32_e32 v30, v15
	v_rcp_f32_e32 v42, v31
	v_mul_f32_e32 v29, v65, v14
	v_mul_f32_e32 v39, v61, v14
	v_mul_f32_e32 v37, v64, v14
	v_mul_f32_e32 v41, v60, v14
	s_waitcnt lgkmcnt(0)
; __device__ __forceinline__ unsigned pk2(float lo, float hi) { return pg8::cvt_pk_bf16(lo, hi); }
; __device__ __forceinline__ float siluf_(float v) { return v * __builtin_amdgcn_rcpf(1.f + __builtin_amdgcn_exp2f(-LOG2E * v)); }
; __device__ __forceinline__ void attn_unit(int b, int h, int qb, bf16_t* Q, const bf16_t* __restrict__ K, const bf16_t* __restrict__ Vt, const bf16_t* __restrict__ Z, const float* __restrict__ hg, float lam, ...
;     ...
;         for (int ip = 0; ip < 2; ++ip) { __builtin_amdgcn_sched_barrier(0);
;             u32x2 w[2];
;             const u32x4 zl = *(const u32x4*)(Z + offw + 32 * d + 16 * ip + 8 * hi_l);
;             const unsigned zsx = hi_l ? zl.x : zl.z, zsy = hi_l ? zl.y : zl.w;
;             const unsigned zrx = __shfl_xor(zsx, 32), zry = __shfl_xor(zsy, 32);
; #pragma unroll
;             for (int k = 0; k < 2; ++k) { const int i = 2 * ip + k, e = 32 * d + 8 * i;
;                 const f32x4 g4 = *(const f32x4*)(hg + e + 4 * hi_l);
;                 const u32x2 z2 = (k == 0) ? (hi_l ? (u32x2){zrx, zry} : (u32x2){zl.x, zl.y}) : (hi_l ? (u32x2){zl.z, zl.w} : (u32x2){zrx, zry});
;                 const float v0 = o[0][d][4 * i] * rs * g4[0] * siluf_(bflo(z2.x)), v1 = o[0][d][4 * i + 1] * rs * g4[1] * siluf_(bfhi(z2.x));
;                 const float v2 = o[0][d][4 * i + 2] * rs * g4[2] * siluf_(bflo(z2.y)), v3 = o[0][d][4 * i + 3] * rs * g4[3] * siluf_(bfhi(z2.y));
;                 w[k] = (u32x2){pk2(v0, v1), pk2(v2, v3)}; }
;             const u32x2 snd = hi_l ? w[0] : w[1];
;             const unsigned rx = __shfl_xor(snd.x, 32), ry = __shfl_xor(snd.y, 32);
;             const u32x4 st = hi_l ? (u32x4){rx, ry, w[1].x, w[1].y} : (u32x4){w[0].x, w[0].y, rx, ry};
;             *(u32x4*)(Q + offw + 32 * d + 16 * ip + 8 * hi_l) = st; }
	v_mov_b32_e32 v31, v32
	v_rcp_f32_e32 v32, v43
	v_mov_b32_e32 v43, v34
	v_rcp_f32_e32 v34, v46
	v_pk_mul_f32 v[28:29], v[30:31], v[28:29]
	v_pk_mul_f32 v[30:31], v[42:43], v[38:39]
	v_mul_f32_e32 v15, v28, v29
	v_mul_f32_e32 v38, v30, v31
	v_pk_mul_f32 v[28:29], v[32:33], v[36:37]
	v_pk_mul_f32 v[30:31], v[34:35], v[40:41]
	v_mul_f32_e32 v28, v28, v29
	v_mul_f32_e32 v29, v30, v31
	v_cvt_pk_bf16_f32 v15, v15, v28
	v_cvt_pk_bf16_f32 v29, v38, v29
	s_nop 0
	v_mov_b32_e32 v31, v29
	v_mov_b32_e32 v30, v15
	v_mov_b32_e32 v28, v44
	v_mov_b32_e32 v29, v45
	s_nop 1
	v_permlane32_swap_b32_e32 v28, v30
	v_permlane32_swap_b32_e32 v29, v31
	global_store_dwordx4 v[8:9], v[28:31], off offset:96
	s_nop 0
	ds_read_b128 v[32:35], v137 offset:256
	v_mul_f32_e32 v41, v57, v14
	v_mul_f32_e32 v37, v59, v14
	v_mul_f32_e32 v39, v58, v14
	v_mul_f32_e32 v43, v56, v14
	s_waitcnt vmcnt(7)
	v_mov_b32_e32 v28, v162
	v_mov_b32_e32 v29, v163
	v_mov_b32_e32 v30, v164
	v_mov_b32_e32 v31, v165
	s_nop 1
	v_permlane32_swap_b32_e32 v28, v30
	v_permlane32_swap_b32_e32 v29, v31
	s_waitcnt lgkmcnt(0)
	v_mov_b32_e32 v45, v32
	v_mov_b32_e32 v47, v34
	v_lshlrev_b32_e32 v36, 16, v28
	v_and_b32_e32 v38, 0xffff0000, v28
	v_lshlrev_b32_e32 v40, 16, v29
	v_and_b32_e32 v42, 0xffff0000, v29
	v_mul_f32_e32 v28, 0xbfb8aa3b, v36
	v_mul_f32_e32 v29, 0xbfb8aa3b, v38
	v_mul_f32_e32 v32, 0xbfb8aa3b, v40
	v_mul_f32_e32 v34, 0xbfb8aa3b, v42
	v_exp_f32_e32 v28, v28
	v_exp_f32_e32 v29, v29
	v_exp_f32_e32 v32, v32
	v_exp_f32_e32 v34, v34
	v_add_f32_e32 v28, 1.0, v28
	v_add_f32_e32 v29, 1.0, v29
	v_add_f32_e32 v46, 1.0, v32
	v_add_f32_e32 v34, 1.0, v34
	v_rcp_f32_e32 v44, v28
	v_rcp_f32_e32 v32, v29
	v_rcp_f32_e32 v46, v46
	v_rcp_f32_e32 v34, v34
	v_pk_mul_f32 v[28:29], v[44:45], v[36:37]
	v_pk_mul_f32 v[32:33], v[32:33], v[38:39]
	v_pk_mul_f32 v[36:37], v[46:47], v[40:41]
	v_pk_mul_f32 v[34:35], v[34:35], v[42:43]
	v_mul_f32_e32 v28, v28, v29
	v_mul_f32_e32 v29, v32, v33
	v_mul_f32_e32 v32, v36, v37
	v_mul_f32_e32 v33, v34, v35
	v_cvt_pk_bf16_f32 v44, v28, v29
	v_cvt_pk_bf16_f32 v45, v32, v33
	ds_read_b128 v[32:35], v137 offset:288
	v_mov_b32_e32 v15, v30
	v_lshlrev_b32_e32 v28, 16, v15
	v_lshlrev_b32_e32 v38, 16, v31
	v_and_b32_e32 v36, 0xffff0000, v15
	v_and_b32_e32 v40, 0xffff0000, v31
	v_mul_f32_e32 v15, 0xbfb8aa3b, v28
	v_mul_f32_e32 v31, 0xbfb8aa3b, v38
	v_mul_f32_e32 v30, 0xbfb8aa3b, v36
	v_mul_f32_e32 v42, 0xbfb8aa3b, v40
	v_exp_f32_e32 v15, v15
	v_exp_f32_e32 v31, v31
	v_exp_f32_e32 v30, v30
	v_exp_f32_e32 v42, v42
	v_add_f32_e32 v15, 1.0, v15
	v_add_f32_e32 v31, 1.0, v31
	v_add_f32_e32 v43, 1.0, v30
	v_add_f32_e32 v46, 1.0, v42
	v_rcp_f32_e32 v30, v15
	v_rcp_f32_e32 v42, v31
	v_mul_f32_e32 v29, v55, v14
	v_mul_f32_e32 v39, v53, v14
	v_mul_f32_e32 v37, v54, v14
	v_mul_f32_e32 v41, v52, v14
	s_waitcnt lgkmcnt(0)
	v_mov_b32_e32 v31, v32
	v_rcp_f32_e32 v32, v43
	v_mov_b32_e32 v43, v34
	v_rcp_f32_e32 v34, v46
	v_pk_mul_f32 v[28:29], v[30:31], v[28:29]
	v_pk_mul_f32 v[30:31], v[42:43], v[38:39]
	v_mul_f32_e32 v15, v28, v29
	v_mul_f32_e32 v38, v30, v31
	v_pk_mul_f32 v[28:29], v[32:33], v[36:37]
	v_pk_mul_f32 v[30:31], v[34:35], v[40:41]
	v_mul_f32_e32 v28, v28, v29
	v_mul_f32_e32 v29, v30, v31
	v_cvt_pk_bf16_f32 v15, v15, v28
	v_cvt_pk_bf16_f32 v29, v38, v29
	s_nop 0
	v_mov_b32_e32 v31, v29
	v_mov_b32_e32 v30, v15
	v_mov_b32_e32 v28, v44
	v_mov_b32_e32 v29, v45
	s_nop 1
	v_permlane32_swap_b32_e32 v28, v30
	v_permlane32_swap_b32_e32 v29, v31
	global_store_dwordx4 v[8:9], v[28:31], off offset:128
	s_nop 0
	ds_read_b128 v[32:35], v137 offset:320
	v_mul_f32_e32 v42, v48, v14
	v_mul_f32_e32 v40, v49, v14
	v_mul_f32_e32 v36, v51, v14
	v_mul_f32_e32 v38, v50, v14
	v_mul_f32_e32 v26, v26, v14
	v_mul_f32_e32 v24, v24, v14
	s_waitcnt vmcnt(7)
	v_mov_b32_e32 v28, v166
	v_mov_b32_e32 v29, v167
	v_mov_b32_e32 v30, v168
	v_mov_b32_e32 v31, v169
	s_nop 1
	v_permlane32_swap_b32_e32 v28, v30
	v_permlane32_swap_b32_e32 v29, v31
	s_waitcnt lgkmcnt(0)
	v_mov_b32_e32 v44, v33
	v_mov_b32_e32 v46, v35
	v_lshlrev_b32_e32 v37, 16, v28
	v_and_b32_e32 v39, 0xffff0000, v28
	v_lshlrev_b32_e32 v41, 16, v29
	v_and_b32_e32 v43, 0xffff0000, v29
	v_mul_f32_e32 v28, 0xbfb8aa3b, v37
	v_mul_f32_e32 v29, 0xbfb8aa3b, v39
	v_mul_f32_e32 v33, 0xbfb8aa3b, v41
	v_mul_f32_e32 v35, 0xbfb8aa3b, v43
	v_exp_f32_e32 v28, v28
	v_exp_f32_e32 v29, v29
	v_exp_f32_e32 v33, v33
	v_exp_f32_e32 v35, v35
	v_add_f32_e32 v28, 1.0, v28
	v_add_f32_e32 v29, 1.0, v29
	v_add_f32_e32 v47, 1.0, v33
	v_add_f32_e32 v49, 1.0, v35
	v_rcp_f32_e32 v33, v28
	v_rcp_f32_e32 v45, v29
	v_rcp_f32_e32 v35, v47
	v_rcp_f32_e32 v47, v49
	v_pk_mul_f32 v[28:29], v[32:33], v[36:37]
	v_pk_mul_f32 v[32:33], v[44:45], v[38:39]
	v_pk_mul_f32 v[34:35], v[34:35], v[40:41]
	v_pk_mul_f32 v[36:37], v[46:47], v[42:43]
	v_mul_f32_e32 v28, v28, v29
	v_mul_f32_e32 v29, v32, v33
	v_mul_f32_e32 v32, v34, v35
	v_mul_f32_e32 v33, v36, v37
	v_cvt_pk_bf16_f32 v44, v28, v29
	v_cvt_pk_bf16_f32 v45, v32, v33
	ds_read_b128 v[32:35], v137 offset:352
	v_mul_f32_e32 v36, v25, v14
	v_mov_b32_e32 v25, v31
	v_mov_b32_e32 v15, v30
	v_mul_f32_e32 v28, v27, v14
	v_lshlrev_b32_e32 v29, 16, v15
	v_and_b32_e32 v27, 0xffff0000, v15
	v_lshlrev_b32_e32 v37, 16, v25
	v_and_b32_e32 v25, 0xffff0000, v25
	v_mul_f32_e32 v15, 0xbfb8aa3b, v29
	v_mul_f32_e32 v30, 0xbfb8aa3b, v27
	v_mul_f32_e32 v38, 0xbfb8aa3b, v25
	v_mul_f32_e32 v31, 0xbfb8aa3b, v37
	v_exp_f32_e32 v15, v15
	v_exp_f32_e32 v30, v30
	v_exp_f32_e32 v38, v38
	v_exp_f32_e32 v31, v31
	v_add_f32_e32 v15, 1.0, v15
	v_add_f32_e32 v30, 1.0, v30
	v_add_f32_e32 v38, 1.0, v38
	v_add_f32_e32 v40, 1.0, v31
	v_rcp_f32_e32 v31, v15
	v_rcp_f32_e32 v39, v30
	v_rcp_f32_e32 v43, v38
	v_rcp_f32_e32 v41, v40
	s_waitcnt lgkmcnt(0)
; __device__ __forceinline__ unsigned pk2(float lo, float hi) { return pg8::cvt_pk_bf16(lo, hi); }
; __device__ __forceinline__ float siluf_(float v) { return v * __builtin_amdgcn_rcpf(1.f + __builtin_amdgcn_exp2f(-LOG2E * v)); }
; __device__ __forceinline__ void attn_unit(int b, int h, int qb, bf16_t* Q, const bf16_t* __restrict__ K, const bf16_t* __restrict__ Vt, const bf16_t* __restrict__ Z, const float* __restrict__ hg, float lam, ...
;     ...
;         for (int ip = 0; ip < 2; ++ip) { __builtin_amdgcn_sched_barrier(0);
;             u32x2 w[2];
;             const u32x4 zl = *(const u32x4*)(Z + offw + 32 * d + 16 * ip + 8 * hi_l);
;             const unsigned zsx = hi_l ? zl.x : zl.z, zsy = hi_l ? zl.y : zl.w;
;             const unsigned zrx = __shfl_xor(zsx, 32), zry = __shfl_xor(zsy, 32);
; #pragma unroll
;             for (int k = 0; k < 2; ++k) { const int i = 2 * ip + k, e = 32 * d + 8 * i;
;                 const f32x4 g4 = *(const f32x4*)(hg + e + 4 * hi_l);
;                 const u32x2 z2 = (k == 0) ? (hi_l ? (u32x2){zrx, zry} : (u32x2){zl.x, zl.y}) : (hi_l ? (u32x2){zl.z, zl.w} : (u32x2){zrx, zry});
;                 const float v0 = o[0][d][4 * i] * rs * g4[0] * siluf_(bflo(z2.x)), v1 = o[0][d][4 * i + 1] * rs * g4[1] * siluf_(bfhi(z2.x));
;                 const float v2 = o[0][d][4 * i + 2] * rs * g4[2] * siluf_(bflo(z2.y)), v3 = o[0][d][4 * i + 3] * rs * g4[3] * siluf_(bfhi(z2.y));
;                 w[k] = (u32x2){pk2(v0, v1), pk2(v2, v3)}; }
;             const u32x2 snd = hi_l ? w[0] : w[1];
;             const unsigned rx = __shfl_xor(snd.x, 32), ry = __shfl_xor(snd.y, 32);
;             const u32x4 st = hi_l ? (u32x4){rx, ry, w[1].x, w[1].y} : (u32x4){w[0].x, w[0].y, rx, ry};
;             *(u32x4*)(Q + offw + 32 * d + 16 * ip + 8 * hi_l) = st; }
	v_mov_b32_e32 v30, v32
	v_mov_b32_e32 v38, v33
	v_mov_b32_e32 v42, v35
	v_mov_b32_e32 v40, v34
	v_pk_mul_f32 v[28:29], v[30:31], v[28:29]
	v_pk_mul_f32 v[26:27], v[38:39], v[26:27]
	v_pk_mul_f32 v[24:25], v[42:43], v[24:25]
	v_pk_mul_f32 v[30:31], v[40:41], v[36:37]
	v_mul_f32_e32 v15, v28, v29
	v_mul_f32_e32 v26, v26, v27
	v_mul_f32_e32 v24, v24, v25
	v_mul_f32_e32 v27, v30, v31
	v_cvt_pk_bf16_f32 v15, v15, v26
	v_cvt_pk_bf16_f32 v25, v27, v24
	s_nop 0
	v_mov_b32_e32 v27, v25
	v_mov_b32_e32 v26, v15
	v_mov_b32_e32 v24, v44
	v_mov_b32_e32 v25, v45
	s_nop 1
	v_permlane32_swap_b32_e32 v24, v26
	v_permlane32_swap_b32_e32 v25, v27
	global_store_dwordx4 v[8:9], v[24:27], off offset:160
	s_nop 0
	ds_read_b128 v[28:31], v137 offset:384
	v_mul_f32_e32 v34, v21, v14
	v_mul_f32_e32 v32, v23, v14
	v_mul_f32_e32 v22, v22, v14
	v_mul_f32_e32 v20, v20, v14
	v_mul_f32_e32 v18, v18, v14
	v_mul_f32_e32 v16, v16, v14
	s_waitcnt vmcnt(7)
	v_mov_b32_e32 v24, v170
	v_mov_b32_e32 v25, v171
	v_mov_b32_e32 v26, v172
	v_mov_b32_e32 v27, v173
	s_nop 1
	v_permlane32_swap_b32_e32 v24, v26
	v_permlane32_swap_b32_e32 v25, v27
	s_waitcnt lgkmcnt(0)
	v_mov_b32_e32 v36, v29
	v_mov_b32_e32 v38, v31
	v_mov_b32_e32 v21, v25
	v_mov_b32_e32 v23, v24
	v_lshlrev_b32_e32 v29, 16, v23
	v_and_b32_e32 v37, 0xffff0000, v23
	v_lshlrev_b32_e32 v31, 16, v21
	v_and_b32_e32 v39, 0xffff0000, v21
	v_mul_f32_e32 v21, 0xbfb8aa3b, v29
	v_mul_f32_e32 v23, 0xbfb8aa3b, v37
	v_mul_f32_e32 v24, 0xbfb8aa3b, v31
	v_mul_f32_e32 v25, 0xbfb8aa3b, v39
	v_exp_f32_e32 v21, v21
	v_exp_f32_e32 v23, v23
	v_exp_f32_e32 v24, v24
	v_exp_f32_e32 v25, v25
	v_add_f32_e32 v21, 1.0, v21
	v_add_f32_e32 v23, 1.0, v23
	v_add_f32_e32 v24, 1.0, v24
	v_add_f32_e32 v25, 1.0, v25
	v_rcp_f32_e32 v33, v21
	v_rcp_f32_e32 v23, v23
	v_rcp_f32_e32 v35, v24
	v_rcp_f32_e32 v21, v25
	v_pk_mul_f32 v[24:25], v[32:33], v[28:29]
	v_pk_mul_f32 v[22:23], v[22:23], v[36:37]
	v_pk_mul_f32 v[28:29], v[34:35], v[30:31]
	v_pk_mul_f32 v[20:21], v[20:21], v[38:39]
	v_mul_f32_e32 v22, v22, v23
	v_mul_f32_e32 v23, v28, v29
	v_mul_f32_e32 v20, v20, v21
	v_mul_f32_e32 v24, v24, v25
	v_cvt_pk_bf16_f32 v36, v24, v22
	v_cvt_pk_bf16_f32 v37, v23, v20
	ds_read_b128 v[20:23], v137 offset:416
	v_mul_f32_e32 v28, v17, v14
	v_mov_b32_e32 v17, v27
	v_mov_b32_e32 v15, v26
	v_lshlrev_b32_e32 v27, 16, v15
	v_and_b32_e32 v31, 0xffff0000, v15
	v_and_b32_e32 v35, 0xffff0000, v17
	v_lshlrev_b32_e32 v33, 16, v17
	v_mul_f32_e32 v15, 0xbfb8aa3b, v27
	v_mul_f32_e32 v17, 0xbfb8aa3b, v31
	v_mul_f32_e32 v25, 0xbfb8aa3b, v35
	v_mul_f32_e32 v24, v19, v14
	v_mul_f32_e32 v19, 0xbfb8aa3b, v33
	v_exp_f32_e32 v15, v15
	v_exp_f32_e32 v17, v17
	v_exp_f32_e32 v25, v25
	v_exp_f32_e32 v19, v19
	v_add_f32_e32 v15, 1.0, v15
	v_add_f32_e32 v17, 1.0, v17
	v_add_f32_e32 v30, 1.0, v25
	v_add_f32_e32 v26, 1.0, v19
	v_rcp_f32_e32 v25, v15
	v_rcp_f32_e32 v19, v17
	v_rcp_f32_e32 v17, v30
	v_rcp_f32_e32 v29, v26
	s_waitcnt lgkmcnt(0)
	v_mov_b32_e32 v26, v20
	v_mov_b32_e32 v30, v21
	v_mov_b32_e32 v34, v23
	v_mov_b32_e32 v32, v22
	v_pk_mul_f32 v[20:21], v[24:25], v[26:27]
	v_pk_mul_f32 v[18:19], v[18:19], v[30:31]
	v_pk_mul_f32 v[16:17], v[16:17], v[34:35]
	v_pk_mul_f32 v[22:23], v[28:29], v[32:33]
	v_mul_f32_e32 v15, v20, v21
	v_mul_f32_e32 v18, v18, v19
	v_mul_f32_e32 v16, v16, v17
	v_mul_f32_e32 v19, v22, v23
	v_cvt_pk_bf16_f32 v15, v15, v18
	v_cvt_pk_bf16_f32 v17, v19, v16
	s_nop 0
	v_mov_b32_e32 v19, v17
	v_mov_b32_e32 v18, v15
	v_mov_b32_e32 v16, v36
	v_mov_b32_e32 v17, v37
	s_nop 1
	v_permlane32_swap_b32_e32 v16, v18
	v_permlane32_swap_b32_e32 v17, v19
	global_store_dwordx4 v[8:9], v[16:19], off offset:192
	s_nop 0
	ds_read_b128 v[20:23], v137 offset:448
	v_mul_f32_e32 v12, v7, v14
	v_mul_f32_e32 v24, v5, v14
	v_mul_f32_e32 v6, v6, v14
	v_mul_f32_e32 v4, v4, v14
	v_mul_f32_e32 v2, v2, v14
	v_mul_f32_e32 v0, v0, v14
	s_mov_b64 s[8:9], 0
	s_waitcnt vmcnt(7)
	v_mov_b32_e32 v16, v174
	v_mov_b32_e32 v17, v175
	v_mov_b32_e32 v18, v176
	v_mov_b32_e32 v19, v177
	s_nop 1
	v_permlane32_swap_b32_e32 v16, v18
	v_permlane32_swap_b32_e32 v17, v19
	s_waitcnt lgkmcnt(0)
	v_mov_b32_e32 v26, v21
	v_mov_b32_e32 v28, v23
	v_mov_b32_e32 v5, v17
	v_mov_b32_e32 v7, v16
	v_lshlrev_b32_e32 v21, 16, v7
	v_and_b32_e32 v27, 0xffff0000, v7
	v_lshlrev_b32_e32 v23, 16, v5
	v_and_b32_e32 v29, 0xffff0000, v5
	v_mul_f32_e32 v5, 0xbfb8aa3b, v21
	v_mul_f32_e32 v7, 0xbfb8aa3b, v27
	v_mul_f32_e32 v13, 0xbfb8aa3b, v23
	v_mul_f32_e32 v16, 0xbfb8aa3b, v29
	v_exp_f32_e32 v5, v5
	v_exp_f32_e32 v7, v7
	v_exp_f32_e32 v13, v13
	v_exp_f32_e32 v16, v16
	v_add_f32_e32 v5, 1.0, v5
	v_add_f32_e32 v7, 1.0, v7
	v_add_f32_e32 v17, 1.0, v13
	v_add_f32_e32 v16, 1.0, v16
	v_rcp_f32_e32 v13, v5
	v_rcp_f32_e32 v7, v7
	v_rcp_f32_e32 v25, v17
	v_rcp_f32_e32 v5, v16
	v_pk_mul_f32 v[12:13], v[12:13], v[20:21]
	v_pk_mul_f32 v[6:7], v[6:7], v[26:27]
	v_pk_mul_f32 v[16:17], v[24:25], v[22:23]
	v_pk_mul_f32 v[4:5], v[4:5], v[28:29]
	v_mul_f32_e32 v6, v6, v7
	v_mul_f32_e32 v7, v16, v17
	v_mul_f32_e32 v4, v4, v5
	v_mul_f32_e32 v12, v12, v13
	v_cvt_pk_bf16_f32 v22, v12, v6
	v_cvt_pk_bf16_f32 v23, v7, v4
	ds_read_b128 v[4:7], v137 offset:480
	v_mul_f32_e32 v10, v3, v14
	v_mul_f32_e32 v12, v1, v14
	v_mov_b32_e32 v1, v19
	v_mov_b32_e32 v3, v18
	v_lshlrev_b32_e32 v15, 16, v3
	v_and_b32_e32 v17, 0xffff0000, v3
	v_lshlrev_b32_e32 v19, 16, v1
	v_and_b32_e32 v21, 0xffff0000, v1
	v_mul_f32_e32 v1, 0xbfb8aa3b, v15
	v_mul_f32_e32 v3, 0xbfb8aa3b, v17
	v_mul_f32_e32 v11, 0xbfb8aa3b, v19
	v_mul_f32_e32 v13, 0xbfb8aa3b, v21
	v_exp_f32_e32 v1, v1
	v_exp_f32_e32 v3, v3
	v_exp_f32_e32 v11, v11
	v_exp_f32_e32 v13, v13
	v_add_f32_e32 v1, 1.0, v1
	v_add_f32_e32 v14, 1.0, v3
	v_add_f32_e32 v16, 1.0, v11
	v_add_f32_e32 v13, 1.0, v13
	v_rcp_f32_e32 v3, v1
	v_rcp_f32_e32 v11, v14
	v_rcp_f32_e32 v1, v16
	v_rcp_f32_e32 v13, v13
	s_waitcnt lgkmcnt(0)
	v_mov_b32_e32 v14, v4
	v_mov_b32_e32 v16, v5
	v_mov_b32_e32 v18, v6
	v_mov_b32_e32 v20, v7
	v_pk_mul_f32 v[2:3], v[2:3], v[14:15]
	v_pk_mul_f32 v[4:5], v[10:11], v[16:17]
	v_pk_mul_f32 v[0:1], v[0:1], v[18:19]
	v_pk_mul_f32 v[6:7], v[12:13], v[20:21]
	v_mul_f32_e32 v2, v2, v3
	v_mul_f32_e32 v3, v4, v5
	v_mul_f32_e32 v0, v0, v1
	v_mul_f32_e32 v1, v6, v7
	v_cvt_pk_bf16_f32 v2, v2, v3
	v_cvt_pk_bf16_f32 v1, v0, v1
	s_nop 0
	v_mov_b32_e32 v3, v1
	v_mov_b32_e32 v0, v22
	v_mov_b32_e32 v1, v23
	s_nop 1
	v_permlane32_swap_b32_e32 v0, v2
	v_permlane32_swap_b32_e32 v1, v3
	global_store_dwordx4 v[8:9], v[0:3], off offset:224
